# window-branch attention: P.V accumulates in place (no output copies), fewer reduction/compare VALU ops
# baseline (speedup 1.0000x reference)
; #define LAS __attribute__((address_space(3)))
; template <int MODE, bool FAST, bool DEFER>
; __device__ __forceinline__ void attn_tile(AttnState& st, const LAS bf16_t* Ks, const LAS bf16_t* Vt, int jb, int tq, bool mybit, int fr, int fq, float (&imp)[16], float& prev_t3, bf16x8 (&pfo)[2][2]) {
;     ...
;     for (int ct = 0; ct < 2; ++ct) { const float nb_ = !FAST ? 0.f : ((MODE == M_SLC && !mybit) ? -1e30f : (st.m[ct] < -1e29f ? 0.f : -st.m[ct])); zinit[ct] = (f32x4){nb_, nb_, nb_, nb_}; }
; #pragma unroll
;     for (int sb = 0; sb < 4; ++sb) {
;         const bf16x8 k0 = *(const LAS bf16x8*)(Ks + (sb * 16 + fr) * KSTR + fq * 8);
;         const bf16x8 k1 = *(const LAS bf16x8*)(Ks + (sb * 16 + fr) * KSTR + 32 + fq * 8);
; #pragma unroll
;         for (int ct = 0; ct < 2; ++ct) {
;             f32x4 z = zinit[ct];
;             z = __builtin_amdgcn_mfma_f32_16x16x32_bf16(k0, st.qf[ct][0], z, 0, 0, 0);
;             z = __builtin_amdgcn_mfma_f32_16x16x32_bf16(k1, st.qf[ct][1], z, 0, 0, 0);
;             s[ct][sb] = ISCMP ? z * ATT_QS : z;
;         }
;     }
;     unsigned vbits = 0;
;     if (!FAST) {
; #pragma unroll
;         for (int sb = 0; sb < 4; ++sb)
; #pragma unroll
;             for (int j = 0; j < 4; ++j) {
;                 const int kidx = jb * 64 + sb * 16 + fq * 4 + j;
;                 bool v;
;                 if (ISCMP) v = (16 * kidx + 31 <= tq);
;                 else if (MODE == M_SLC) v = mybit && (kidx <= tq);
;                 else v = (kidx <= tq) && (tq - kidx < 512);
;                 vbits |= (v ? 1u : 0u) << (sb * 4 + j);
;             }
;     }
.LBB0_1167:
	s_cmp_lg_u32 s2, s37
	s_cselect_b64 s[0:1], -1, 0
	s_cmp_lg_u32 s2, s14
	s_cselect_b64 s[4:5], -1, 0
	s_and_b64 s[4:5], s[0:1], s[4:5]
	s_mov_b64 s[0:1], -1
	s_andn2_b64 vcc, exec, s[4:5]
	v_add3_u32 v193, v3, v164, v183
	s_waitcnt lgkmcnt(0)
	s_barrier
	s_cbranch_vccz .LBB0_1171
	ds_read_b128 v[60:63], v193
	ds_read_b128 v[64:67], v193 offset:64
	ds_read_b128 v[72:75], v193 offset:2304
	ds_read_b128 v[76:79], v193 offset:2368
	ds_read_b128 v[80:83], v193 offset:4608
	ds_read_b128 v[84:87], v193 offset:4672
	s_waitcnt lgkmcnt(3)
	v_mfma_f32_16x16x32_bf16 v[92:95], v[72:75], v[4:7], 0
	v_lshl_or_b32 v3, s2, 6, v126
	v_cmp_ge_i32_e64 s[2:3], v3, v152
	v_cmp_lt_i32_e64 s[4:5], v3, v161
	v_mfma_f32_16x16x32_bf16 v[72:75], v[72:75], v[12:15], 0
	s_or_b64 s[4:5], s[2:3], s[4:5]
	v_or_b32_e32 v100, 17, v3
	v_or_b32_e32 v101, 18, v3
	v_mfma_f32_16x16x32_bf16 v[68:71], v[60:63], v[4:7], 0
	v_or_b32_e32 v106, 19, v3
	v_or_b32_e32 v107, 32, v3
	v_or_b32_e32 v108, 49, v3
	v_mfma_f32_16x16x32_bf16 v[60:63], v[60:63], v[12:15], 0
	v_cmp_le_i32_e32 vcc, v3, v152
	v_cmp_gt_i32_e64 s[0:1], v3, v161
	s_and_b64 s[68:69], vcc, s[0:1]
	s_waitcnt lgkmcnt(2)
	v_mfma_f32_16x16x32_bf16 v[102:105], v[76:79], v[8:11], v[92:95]
	v_mov_b32_e32 v192, v189
	v_mov_b32_e32 v200, v190
	v_mov_b32_e32 v201, v2
	v_or_b32_e32 v93, 2, v3
	v_cmp_gt_i32_e64 s[2:3], v93, v152
	v_cmp_le_i32_e64 s[6:7], v93, v161
	v_mfma_f32_16x16x32_bf16 v[72:75], v[76:79], v[16:19], v[72:75]
	v_or_b32_e32 v76, 3, v3
	s_or_b64 s[8:9], s[2:3], s[6:7]
	v_cmp_gt_i32_e64 s[2:3], v76, v152
	v_mfma_f32_16x16x32_bf16 v[68:71], v[64:67], v[8:11], v[68:71]
	v_cmp_le_i32_e64 s[6:7], v76, v161
	v_or_b32_e32 v95, 16, v3
	s_or_b64 s[46:47], s[2:3], s[6:7]
	v_mfma_f32_16x16x32_bf16 v[60:63], v[64:67], v[16:19], v[60:63]
	ds_read_b128 v[64:67], v193 offset:6912
	ds_read_b128 v[88:91], v193 offset:6976
	v_cmp_gt_i32_e64 s[2:3], v95, v152
	v_cmp_le_i32_e64 s[6:7], v95, v161
	s_waitcnt lgkmcnt(3)
	v_mfma_f32_16x16x32_bf16 v[76:79], v[80:83], v[4:7], 0
	s_or_b64 s[42:43], s[2:3], s[6:7]
	v_cmp_le_i32_e64 s[2:3], v100, v152
	v_cmp_gt_i32_e64 s[6:7], v100, v161
	v_mfma_f32_16x16x32_bf16 v[80:83], v[80:83], v[12:15], 0
	s_and_b64 s[56:57], s[2:3], s[6:7]
	v_cmp_le_i32_e64 s[2:3], v101, v152
	v_cmp_gt_i32_e64 s[6:7], v101, v161
	s_waitcnt lgkmcnt(2)
	v_mfma_f32_16x16x32_bf16 v[76:79], v[84:87], v[8:11], v[76:79]
	s_and_b64 s[52:53], s[2:3], s[6:7]
	v_cmp_gt_i32_e64 s[2:3], v106, v152
	v_cmp_le_i32_e64 s[6:7], v106, v161
	v_mfma_f32_16x16x32_bf16 v[80:83], v[84:87], v[16:19], v[80:83]
	s_or_b64 s[62:63], s[2:3], s[6:7]
	v_cmp_gt_i32_e64 s[2:3], v107, v152
	v_cmp_le_i32_e64 s[6:7], v107, v161
	s_waitcnt lgkmcnt(1)
	v_mfma_f32_16x16x32_bf16 v[84:87], v[64:67], v[4:7], 0
	s_or_b64 s[58:59], s[2:3], s[6:7]
	v_or_b32_e32 v107, 48, v3
	v_cndmask_b32_e64 v92, 2, 0, s[4:5]
	v_mfma_f32_16x16x32_bf16 v[64:67], v[64:67], v[12:15], 0
	v_cndmask_b32_e64 v93, 4, 0, s[8:9]
	v_cndmask_b32_e64 v106, v218, 0, s[62:63]
	v_cndmask_b32_e64 v94, 8, 0, s[46:47]
	s_waitcnt lgkmcnt(0)
; template <int MODE, bool FAST, bool DEFER>
; __device__ __forceinline__ void attn_tile(AttnState& st, const LAS bf16_t* Ks, const LAS bf16_t* Vt, int jb, int tq, bool mybit, int fr, int fq, float (&imp)[16], float& prev_t3, bf16x8 (&pfo)[2][2]) {
;     ...
;     float tmaxv[2]; bool need[2];
; #pragma unroll
;     for (int ct = 0; ct < 2; ++ct) {
;         float tmax = -1e30f;
; #pragma unroll
;         for (int sb = 0; sb < 4; ++sb)
; #pragma unroll
;             for (int j = 0; j < 4; ++j) {
;                 if (!FAST) s[ct][sb][j] = ((vbits >> (sb * 4 + j)) & 1u) ? s[ct][sb][j] : -1e30f;
;                 tmax = fmaxf(tmax, s[ct][sb][j]);
;             }
;         if (FAST && MODE == M_SLC) tmax = mybit ? tmax : -1e30f;
;         tmax = fmaxf(tmax, __shfl_xor(tmax, 16)); tmax = fmaxf(tmax, __shfl_xor(tmax, 32));
;         tmaxv[ct] = tmax; need[ct] = tmax > st.m[ct] + ATT_THR;
;     }
;     if (__builtin_amdgcn_ballot_w64(need[0] || need[1]) != 0ull) {
; #pragma unroll
;         for (int ct = 0; ct < 2; ++ct) {
;             const float alpha = need[ct] ? __builtin_amdgcn_exp2f(st.m[ct] - tmaxv[ct]) : 1.f;
;             st.m[ct] = need[ct] ? tmaxv[ct] : st.m[ct];
;             st.l[ct] *= alpha;
;             if (MODE != M_CMP1) {
; #pragma unroll
;                 for (int dt = 0; dt < 4; ++dt) st.o[ct][dt] = st.o[ct][dt] * alpha;
;             }
;         }
	v_mfma_f32_16x16x32_bf16 v[84:87], v[88:91], v[8:11], v[84:87]
	v_cndmask_b32_e64 v95, 16, 0, s[42:43]
	v_cndmask_b32_e64 v100, 0, 32, s[56:57]
	v_cndmask_b32_e64 v101, 0, 64, s[52:53]
	v_mfma_f32_16x16x32_bf16 v[64:67], v[88:91], v[16:19], v[64:67]
	v_or_b32_e32 v89, 33, v3
	v_cmp_le_i32_e64 s[2:3], v89, v152
	v_cmp_gt_i32_e64 s[6:7], v89, v161
	v_or_b32_e32 v90, 34, v3
	s_and_b64 s[60:61], s[2:3], s[6:7]
	v_cmp_le_i32_e64 s[2:3], v90, v152
	v_cmp_gt_i32_e64 s[6:7], v90, v161
	v_or_b32_e32 v91, 35, v3
	s_and_b64 s[50:51], s[2:3], s[6:7]
	v_cmp_gt_i32_e64 s[2:3], v91, v152
	v_cmp_le_i32_e64 s[6:7], v91, v161
	s_or_b64 s[54:55], s[2:3], s[6:7]
	v_cmp_gt_i32_e64 s[2:3], v107, v152
	v_cmp_le_i32_e64 s[6:7], v107, v161
	s_or_b64 s[44:45], s[2:3], s[6:7]
	v_cmp_gt_i32_e64 s[2:3], v108, v152
	v_cmp_le_i32_e64 s[6:7], v108, v161
	v_cndmask_b32_e64 v89, 0, v220, s[60:61]
	v_cndmask_b32_e64 v90, 0, v221, s[50:51]
	s_or_b64 s[48:49], s[2:3], s[6:7]
	v_cndmask_b32_e64 v88, v219, 0, s[58:59]
	v_cndmask_b32_e64 v108, v224, 0, s[48:49]
	v_or3_b32 v89, v90, v92, v89
	v_or3_b32 v88, v89, v88, v108
	v_or_b32_e32 v89, 50, v3
	v_cmp_le_i32_e64 s[2:3], v89, v152
	v_cmp_gt_i32_e64 s[6:7], v89, v161
	s_and_b64 s[2:3], s[2:3], s[6:7]
	v_or_b32_e32 v3, 51, v3
	v_or3_b32 v88, v93, v106, v88
	v_cndmask_b32_e64 v89, 0, v225, s[2:3]
	v_cmp_le_i32_e64 s[2:3], v3, v152
	v_cmp_gt_i32_e64 s[6:7], v3, v161
	v_or3_b32 v88, v94, v95, v88
	s_and_b64 s[2:3], s[2:3], s[6:7]
	v_cndmask_b32_e64 v91, v222, 0, s[54:55]
	v_cndmask_b32_e64 v107, v223, 0, s[44:45]
	v_or3_b32 v88, v100, v101, v88
	v_cndmask_b32_e64 v3, 0, v226, s[2:3]
	v_or3_b32 v88, v107, v91, v88
	v_or_b32_e32 v3, v89, v3
	v_cndmask_b32_e64 v92, v69, v227, s[4:5]
	v_bitop3_b32 v69, v3, s34, v88 bitop3:0xc8
	v_bitop3_b32 v3, v3, s35, v88 bitop3:0xc8
	v_cndmask_b32_e64 v93, v227, v68, s[68:69]
	v_cmp_eq_u32_e64 s[66:67], 0, v3
	v_cndmask_b32_e64 v112, v227, v60, s[68:69]
	v_cndmask_b32_e64 v3, v61, v227, s[4:5]
	v_max3_f32 v68, v93, s36, v92
	v_cndmask_b32_e64 v95, v70, v227, s[8:9]
	v_cndmask_b32_e64 v94, v71, v227, s[46:47]
	v_max3_f32 v60, v112, s36, v3
	v_cndmask_b32_e64 v115, v62, v227, s[8:9]
	v_cndmask_b32_e64 v114, v63, v227, s[46:47]
	v_max3_f32 v68, v68, v95, v94
	v_cndmask_b32_e64 v101, v102, v227, s[42:43]
	v_cndmask_b32_e64 v100, v227, v103, s[56:57]
	v_max3_f32 v60, v60, v115, v114
	v_cndmask_b32_e64 v117, v72, v227, s[42:43]
	v_cndmask_b32_e64 v116, v227, v73, s[56:57]
	v_max3_f32 v68, v68, v101, v100
	v_cndmask_b32_e64 v103, v227, v104, s[52:53]
	v_cndmask_b32_e64 v102, v105, v227, s[62:63]
	v_max3_f32 v60, v60, v117, v116
	v_cndmask_b32_e64 v119, v227, v74, s[52:53]
	v_cndmask_b32_e64 v118, v75, v227, s[62:63]
	v_max3_f32 v68, v68, v103, v102
	v_cndmask_b32_e64 v105, v76, v227, s[58:59]
	v_cndmask_b32_e64 v104, v227, v77, s[60:61]
	v_max3_f32 v60, v60, v119, v118
	v_cndmask_b32_e64 v121, v80, v227, s[58:59]
	v_cndmask_b32_e64 v120, v227, v81, s[60:61]
	v_max3_f32 v68, v68, v105, v104
	v_cndmask_b32_e64 v107, v227, v78, s[50:51]
	v_cndmask_b32_e64 v106, v79, v227, s[54:55]
	v_max3_f32 v60, v60, v121, v120
	v_cndmask_b32_e64 v123, v227, v82, s[50:51]
	v_cndmask_b32_e64 v122, v83, v227, s[54:55]
	v_max3_f32 v68, v68, v107, v106
	v_cndmask_b32_e64 v109, v84, v227, s[44:45]
	v_cndmask_b32_e64 v108, v85, v227, s[48:49]
	v_cmp_eq_u32_e64 s[64:65], 0, v69
	v_max3_f32 v60, v60, v123, v122
	v_cndmask_b32_e64 v157, v64, v227, s[44:45]
	v_cndmask_b32_e64 v156, v65, v227, s[48:49]
	v_max3_f32 v68, v68, v109, v108
	v_cndmask_b32_e64 v111, v86, v227, s[64:65]
	v_cndmask_b32_e64 v110, v87, v227, s[66:67]
	v_max3_f32 v60, v60, v157, v156
	v_cndmask_b32_e64 v159, v66, v227, s[64:65]
	v_cndmask_b32_e64 v158, v67, v227, s[66:67]
	v_max3_f32 v68, v68, v111, v110
	v_max3_f32 v60, v60, v159, v158
	ds_bpermute_b32 v69, v185, v68
	ds_bpermute_b32 v61, v185, v60
	s_waitcnt lgkmcnt(1)
	v_max_f32_e32 v62, v69, v69
	s_waitcnt lgkmcnt(0)
	v_max_f32_e32 v61, v61, v61
	v_max_f32_e32 v62, v68, v62
	v_max_f32_e32 v60, v60, v61
	ds_bpermute_b32 v63, v153, v62
	ds_bpermute_b32 v61, v153, v60
	s_waitcnt lgkmcnt(1)
	v_max_f32_e32 v63, v63, v63
	s_waitcnt lgkmcnt(0)
	v_max_f32_e32 v61, v61, v61
	v_max_f32_e32 v203, v62, v63
	v_add_f32_e32 v62, 0x40c00000, v189
	v_max_f32_e32 v202, v60, v61
	v_add_f32_e32 v60, 0x40c00000, v190
	v_cmp_gt_f32_e64 s[6:7], v203, v62
	v_cmp_gt_f32_e64 s[0:1], v202, v60
	s_or_b64 vcc, s[6:7], s[0:1]
	v_mov_b32_e32 v113, v191
	s_cbranch_vccz .LBB0_1170
	v_sub_f32_e32 v60, v189, v203
	v_exp_f32_e32 v60, v60
	v_cndmask_b32_e64 v192, v189, v203, s[6:7]
	v_cndmask_b32_e64 v200, v190, v202, s[0:1]
	v_cndmask_b32_e64 v60, 1.0, v60, s[6:7]
	v_pk_mul_f32 v[38:39], v[38:39], v[60:61] op_sel_hi:[1,0]
	v_pk_mul_f32 v[36:37], v[36:37], v[60:61] op_sel_hi:[1,0]
	v_pk_mul_f32 v[50:51], v[50:51], v[60:61] op_sel_hi:[1,0]
	v_pk_mul_f32 v[48:49], v[48:49], v[60:61] op_sel_hi:[1,0]
	v_pk_mul_f32 v[54:55], v[54:55], v[60:61] op_sel_hi:[1,0]
	v_pk_mul_f32 v[52:53], v[52:53], v[60:61] op_sel_hi:[1,0]
	v_sub_f32_e32 v61, v190, v202
	v_exp_f32_e32 v64, v61
	v_mul_f32_e32 v113, v191, v60
	v_pk_mul_f32 v[58:59], v[58:59], v[60:61] op_sel_hi:[1,0]
	v_pk_mul_f32 v[56:57], v[56:57], v[60:61] op_sel_hi:[1,0]
	v_cndmask_b32_e64 v64, 1.0, v64, s[0:1]
	v_mul_f32_e32 v201, v2, v64
	v_pk_mul_f32 v[22:23], v[22:23], v[64:65] op_sel_hi:[1,0]
	v_pk_mul_f32 v[20:21], v[20:21], v[64:65] op_sel_hi:[1,0]
	v_pk_mul_f32 v[26:27], v[26:27], v[64:65] op_sel_hi:[1,0]
	v_pk_mul_f32 v[24:25], v[24:25], v[64:65] op_sel_hi:[1,0]
	v_pk_mul_f32 v[30:31], v[30:31], v[64:65] op_sel_hi:[1,0]
	v_pk_mul_f32 v[28:29], v[28:29], v[64:65] op_sel_hi:[1,0]
	v_pk_mul_f32 v[34:35], v[34:35], v[64:65] op_sel_hi:[1,0]
	v_pk_mul_f32 v[32:33], v[32:33], v[64:65] op_sel_hi:[1,0]

; #define LAS __attribute__((address_space(3)))
; template <int MODE, bool FAST, bool DEFER>
; __device__ __forceinline__ void attn_tile(AttnState& st, const LAS bf16_t* Ks, const LAS bf16_t* Vt, int jb, int tq, bool mybit, int fr, int fq, float (&imp)[16], float& prev_t3, bf16x8 (&pfo)[2][2]) {
;     ...
;     for (int ct = 0; ct < 2; ++ct) { const float nb_ = !FAST ? 0.f : ((MODE == M_SLC && !mybit) ? -1e30f : (st.m[ct] < -1e29f ? 0.f : -st.m[ct])); zinit[ct] = (f32x4){nb_, nb_, nb_, nb_}; }
; #pragma unroll
;     for (int sb = 0; sb < 4; ++sb) {
;         const bf16x8 k0 = *(const LAS bf16x8*)(Ks + (sb * 16 + fr) * KSTR + fq * 8);
;         const bf16x8 k1 = *(const LAS bf16x8*)(Ks + (sb * 16 + fr) * KSTR + 32 + fq * 8);
; #pragma unroll
;         for (int ct = 0; ct < 2; ++ct) {
;             f32x4 z = zinit[ct];
;             z = __builtin_amdgcn_mfma_f32_16x16x32_bf16(k0, st.qf[ct][0], z, 0, 0, 0);
;             z = __builtin_amdgcn_mfma_f32_16x16x32_bf16(k1, st.qf[ct][1], z, 0, 0, 0);
;             s[ct][sb] = ISCMP ? z * ATT_QS : z;
;         }
;     }
;     ...
;     if (FAST) {
;         float tz[2]; bool nd[2]; bool un[2];
; #pragma unroll
;         for (int ct = 0; ct < 2; ++ct) {
;             float t = -1e30f;
; #pragma unroll
;             for (int sb = 0; sb < 4; ++sb)
; #pragma unroll
;                 for (int j = 0; j < 4; ++j) t = fmaxf(t, s[ct][sb][j]);
;             t = fmaxf(t, __shfl_xor(t, 16)); t = fmaxf(t, __shfl_xor(t, 32));
;             tz[ct] = t; un[ct] = st.m[ct] < -1e29f;
;             nd[ct] = (t > -1e29f) && (t > ATT_THR || un[ct]);
;         }
;         if (__builtin_amdgcn_ballot_w64(nd[0] || nd[1]) != 0ull) {
; #pragma unroll
;             for (int ct = 0; ct < 2; ++ct) {
;                 const float dl = nd[ct] ? tz[ct] : 0.f;
;                 const float alpha = nd[ct] ? (un[ct] ? 0.f : __builtin_amdgcn_exp2f(-tz[ct])) : 1.f;
;                 st.m[ct] = nd[ct] ? ((un[ct] ? 0.f : st.m[ct]) + tz[ct]) : st.m[ct];
;                 st.l[ct] *= alpha;
; #pragma unroll
;                 for (int dt = 0; dt < 4; ++dt) st.o[ct][dt] = st.o[ct][dt] * alpha;
; #pragma unroll
;                 for (int sb = 0; sb < 4; ++sb) s[ct][sb] = s[ct][sb] - dl;
;             }
.LBB0_1171:
	s_and_b64 vcc, exec, s[0:1]
	s_cbranch_vccz .LBB0_1183
	ds_read_b128 v[60:63], v193
	ds_read_b128 v[64:67], v193 offset:64
	v_cmp_gt_f32_e64 s[4:5], s96, v189
	v_cmp_gt_f32_e64 s[0:1], s96, v190
	s_mov_b64 s[2:3], 0
	v_cndmask_b32_e64 v68, -v189, 0, s[4:5]
	v_cndmask_b32_e64 v92, -v190, 0, s[0:1]
	v_mov_b32_e32 v69, v68
	v_mov_b32_e32 v70, v68
	v_mov_b32_e32 v71, v68
	v_mov_b32_e32 v93, v92
	v_mov_b32_e32 v94, v92
	v_mov_b32_e32 v95, v92
	s_waitcnt lgkmcnt(1)
	v_mfma_f32_16x16x32_bf16 v[72:75], v[60:63], v[4:7], v[68:71]
	s_mov_b64 s[6:7], 0
	v_mfma_f32_16x16x32_bf16 v[60:63], v[60:63], v[12:15], v[92:95]
	s_waitcnt lgkmcnt(0)
	v_mfma_f32_16x16x32_bf16 v[80:83], v[64:67], v[8:11], v[72:75]
	v_mfma_f32_16x16x32_bf16 v[72:75], v[64:67], v[16:19], v[60:63]
	s_nop 4
	ds_read_b128 v[60:63], v193 offset:2304
	ds_read_b128 v[64:67], v193 offset:2368
	v_max3_f32 v3, v80, s36, v81
	v_max3_f32 v3, v3, v82, v83
	s_waitcnt lgkmcnt(1)
	v_mfma_f32_16x16x32_bf16 v[76:79], v[60:63], v[4:7], v[68:71]
	v_mfma_f32_16x16x32_bf16 v[60:63], v[60:63], v[12:15], v[92:95]
	s_waitcnt lgkmcnt(0)
	v_mfma_f32_16x16x32_bf16 v[84:87], v[64:67], v[8:11], v[76:79]
	v_mfma_f32_16x16x32_bf16 v[64:67], v[64:67], v[16:19], v[60:63]
	s_nop 4
	ds_read_b128 v[60:63], v193 offset:4608
	ds_read_b128 v[88:91], v193 offset:4672
	ds_read_b128 v[100:103], v193 offset:6912
	ds_read_b128 v[104:107], v193 offset:6976
	v_max3_f32 v3, v3, v84, v85
	s_waitcnt lgkmcnt(3)
	v_mfma_f32_16x16x32_bf16 v[76:79], v[60:63], v[4:7], v[68:71]
	v_max3_f32 v3, v3, v86, v87
	v_mfma_f32_16x16x32_bf16 v[60:63], v[60:63], v[12:15], v[92:95]
	s_waitcnt lgkmcnt(1)
	v_mfma_f32_16x16x32_bf16 v[68:71], v[100:103], v[4:7], v[68:71]
	v_mfma_f32_16x16x32_bf16 v[76:79], v[88:91], v[8:11], v[76:79]
	v_mfma_f32_16x16x32_bf16 v[60:63], v[88:91], v[16:19], v[60:63]
	s_waitcnt lgkmcnt(0)
	v_mfma_f32_16x16x32_bf16 v[88:91], v[104:107], v[8:11], v[68:71]
	s_nop 4
	v_max3_f32 v3, v3, v76, v77
	v_max3_f32 v3, v3, v78, v79
	v_mfma_f32_16x16x32_bf16 v[68:71], v[100:103], v[12:15], v[92:95]
	v_mfma_f32_16x16x32_bf16 v[68:71], v[104:107], v[16:19], v[68:71]
	v_max3_f32 v3, v3, v88, v89
	v_max3_f32 v3, v3, v90, v91
	ds_bpermute_b32 v92, v185, v3
	s_waitcnt lgkmcnt(0)
	v_max_f32_e32 v3, v3, v92
	ds_bpermute_b32 v92, v153, v3
	s_waitcnt lgkmcnt(0)
	v_max_f32_e32 v92, v3, v92
	v_cmp_lt_f32_e32 vcc, s96, v92
	s_and_saveexec_b64 s[8:9], vcc
	s_cbranch_execz .LBB0_1176
	v_cmp_nlt_f32_e32 vcc, s95, v92
	s_mov_b64 s[6:7], -1
	s_and_saveexec_b64 s[12:13], vcc
	s_orn2_b64 s[6:7], s[4:5], exec
	s_or_b64 exec, exec, s[12:13]
	s_and_b64 s[6:7], s[6:7], exec
.LBB0_1176:
	s_or_b64 exec, exec, s[8:9]
	v_max3_f32 v3, v72, s36, v73
	v_max3_f32 v3, v3, v74, v75
	v_max3_f32 v3, v3, v64, v65
	v_max3_f32 v3, v3, v66, v67
	v_max3_f32 v3, v3, v60, v61
	v_max3_f32 v3, v3, v62, v63
	v_max3_f32 v3, v3, v68, v69
	v_max3_f32 v3, v3, v70, v71
	ds_bpermute_b32 v93, v185, v3
	s_waitcnt lgkmcnt(0)
	v_max_f32_e32 v3, v3, v93
	ds_bpermute_b32 v93, v153, v3
	s_waitcnt lgkmcnt(0)
	v_max_f32_e32 v3, v3, v93
	v_cmp_lt_f32_e32 vcc, s96, v3
	s_and_saveexec_b64 s[8:9], vcc
	s_cbranch_execz .LBB0_1180
	v_cmp_nlt_f32_e32 vcc, s95, v3
	s_mov_b64 s[2:3], -1
	s_and_saveexec_b64 s[12:13], vcc
	s_orn2_b64 s[2:3], s[0:1], exec
	s_or_b64 exec, exec, s[12:13]
	s_and_b64 s[2:3], s[2:3], exec
.LBB0_1180:
	s_or_b64 exec, exec, s[8:9]
	s_or_b64 s[8:9], s[6:7], s[2:3]
	s_and_b64 vcc, exec, s[8:9]
	s_cbranch_vccz .LBB0_1182
	v_exp_f32_e64 v93, -v92
	v_cndmask_b32_e64 v95, v189, 0, s[4:5]
	v_cndmask_b32_e64 v94, 0, v92, s[6:7]
	v_add_f32_e32 v95, v95, v92
	v_cndmask_b32_e64 v92, v93, 0, s[4:5]
	v_cndmask_b32_e64 v92, 1.0, v92, s[6:7]
	v_mul_f32_e32 v191, v191, v92
	v_pk_mul_f32 v[38:39], v[38:39], v[92:93] op_sel_hi:[1,0]
	v_pk_mul_f32 v[36:37], v[36:37], v[92:93] op_sel_hi:[1,0]
	v_pk_mul_f32 v[50:51], v[50:51], v[92:93] op_sel_hi:[1,0]
	v_pk_mul_f32 v[48:49], v[48:49], v[92:93] op_sel_hi:[1,0]
	v_pk_mul_f32 v[54:55], v[54:55], v[92:93] op_sel_hi:[1,0]
	v_pk_mul_f32 v[52:53], v[52:53], v[92:93] op_sel_hi:[1,0]
	v_pk_mul_f32 v[58:59], v[58:59], v[92:93] op_sel_hi:[1,0]
	v_pk_mul_f32 v[56:57], v[56:57], v[92:93] op_sel_hi:[1,0]
	v_exp_f32_e64 v92, -v3
	v_sub_f32_e32 v80, v80, v94
	v_sub_f32_e32 v81, v81, v94
	v_sub_f32_e32 v82, v82, v94
	v_sub_f32_e32 v83, v83, v94
	v_sub_f32_e32 v84, v84, v94
	v_sub_f32_e32 v85, v85, v94
	v_sub_f32_e32 v86, v86, v94
	v_sub_f32_e32 v87, v87, v94
	v_sub_f32_e32 v76, v76, v94
	v_sub_f32_e32 v77, v77, v94
	v_sub_f32_e32 v78, v78, v94
	v_sub_f32_e32 v79, v79, v94
	v_sub_f32_e32 v88, v88, v94
	v_sub_f32_e32 v89, v89, v94
	v_sub_f32_e32 v90, v90, v94
	v_sub_f32_e32 v91, v91, v94
	v_cndmask_b32_e64 v92, v92, 0, s[0:1]
	v_cndmask_b32_e64 v94, v190, 0, s[0:1]
	v_cndmask_b32_e64 v93, 0, v3, s[2:3]
	v_cndmask_b32_e64 v92, 1.0, v92, s[2:3]
	v_add_f32_e32 v3, v94, v3
	v_cndmask_b32_e64 v189, v189, v95, s[6:7]
	v_cndmask_b32_e64 v190, v190, v3, s[2:3]
	v_mul_f32_e32 v2, v2, v92
	v_pk_mul_f32 v[22:23], v[22:23], v[92:93] op_sel_hi:[1,0]
	v_pk_mul_f32 v[20:21], v[20:21], v[92:93] op_sel_hi:[1,0]
	v_pk_mul_f32 v[26:27], v[26:27], v[92:93] op_sel_hi:[1,0]
	v_pk_mul_f32 v[24:25], v[24:25], v[92:93] op_sel_hi:[1,0]
	v_pk_mul_f32 v[30:31], v[30:31], v[92:93] op_sel_hi:[1,0]
	v_pk_mul_f32 v[28:29], v[28:29], v[92:93] op_sel_hi:[1,0]
	v_pk_mul_f32 v[34:35], v[34:35], v[92:93] op_sel_hi:[1,0]
	v_pk_mul_f32 v[32:33], v[32:33], v[92:93] op_sel_hi:[1,0]
	v_sub_f32_e32 v72, v72, v93
	v_sub_f32_e32 v73, v73, v93
	v_sub_f32_e32 v74, v74, v93
	v_sub_f32_e32 v75, v75, v93
	v_sub_f32_e32 v64, v64, v93
	v_sub_f32_e32 v65, v65, v93
	v_sub_f32_e32 v66, v66, v93
	v_sub_f32_e32 v67, v67, v93
	v_sub_f32_e32 v60, v60, v93
	v_sub_f32_e32 v61, v61, v93
	v_sub_f32_e32 v62, v62, v93
	v_sub_f32_e32 v63, v63, v93
	v_sub_f32_e32 v68, v68, v93
	v_sub_f32_e32 v69, v69, v93
	v_sub_f32_e32 v70, v70, v93
	v_sub_f32_e32 v71, v71, v93
; __device__ __forceinline__ unsigned cvt_pk_bf16(float lo, float hi) { const f32x2c v = {lo, hi}; const bf16x2c r = __builtin_convertvector(v, bf16x2c); return __builtin_bit_cast(unsigned, r); }
; #define LAS __attribute__((address_space(3)))
; __device__ __forceinline__ void attn_pv(AttnState& st, const LAS bf16_t* Vt, const bf16x8 (&pf)[2][2], int fr, int fq) {
;     const LAS bf16_t* vb = Vt + (4 * fq + (fr >> 2)) * KSTR + 4 * (fr & 3);
; #pragma unroll
;     for (int kg = 0; kg < 2; ++kg)
; #pragma unroll
;         for (int dt = 0; dt < 4; ++dt) {
;             const s16x4 v0 = __builtin_amdgcn_ds_read_tr16_b64_v4i16((LAS s16x4*)(vb + (kg * 32) * KSTR + dt * 16));
;             const s16x4 v1 = __builtin_amdgcn_ds_read_tr16_b64_v4i16((LAS s16x4*)(vb + (kg * 32 + 16) * KSTR + dt * 16));
;             const bf16x8 vf = {v0[0], v0[1], v0[2], v0[3], v1[0], v1[1], v1[2], v1[3]};
; #pragma unroll
;             for (int ct = 0; ct < 2; ++ct) st.o[ct][dt] = __builtin_amdgcn_mfma_f32_16x16x32_bf16(vf, pf[kg][ct], st.o[ct][dt], 0, 0, 0);
;         }
; template <int MODE, bool FAST, bool DEFER>
; __device__ __forceinline__ void attn_tile(AttnState& st, const LAS bf16_t* Ks, const LAS bf16_t* Vt, int jb, int tq, bool mybit, int fr, int fq, float (&imp)[16], float& prev_t3, bf16x8 (&pfo)[2][2]) {
;     ...
; #pragma unroll
;     for (int ct = 0; ct < 2; ++ct) {
;         const float mu = (FAST && MODE == M_SLC && !mybit) ? 1e30f : st.m[ct];
;         float ls = 0.f;
; #pragma unroll
;         for (int sb = 0; sb < 4; ++sb)
; #pragma unroll
;             for (int j = 0; j < 4; ++j) {
;                 float pe = __builtin_amdgcn_exp2f(s[ct][sb][j] - mu);
;                 if (!FAST) pe = ((vbits >> (sb * 4 + j)) & 1u) ? pe : 0.f;
;                 s[ct][sb][j] = pe; ls += pe;
;             }
;         st.l[ct] += ls;
;     }
;     }
;     if (MODE != M_CMP1) {
; #pragma unroll
;         for (int kg = 0; kg < 2; ++kg)
; #pragma unroll
;             for (int ct = 0; ct < 2; ++ct) { u32x4v w; w.x = cvt_pk_bf16(s[ct][2 * kg][0], s[ct][2 * kg][1]); w.y = cvt_pk_bf16(s[ct][2 * kg][2], s[ct][2 * kg][3]);
;                 w.z = cvt_pk_bf16(s[ct][2 * kg + 1][0], s[ct][2 * kg + 1][1]); w.w = cvt_pk_bf16(s[ct][2 * kg + 1][2], s[ct][2 * kg + 1][3]); pfo[kg][ct] = __builtin_bit_cast(bf16x8, w); }
;         if (!DEFER) attn_pv(st, Vt, pfo, fr, fq);
.LBB0_1182:
	v_exp_f32_e32 v92, v80
	v_exp_f32_e32 v112, v72
	v_exp_f32_e32 v93, v81
	v_exp_f32_e32 v113, v73
	v_exp_f32_e32 v94, v82
	v_exp_f32_e32 v114, v74
	v_exp_f32_e32 v95, v83
	v_exp_f32_e32 v115, v75
	v_exp_f32_e32 v100, v84
	v_exp_f32_e32 v116, v64
	v_add_f32_e32 v3, v93, v92
	v_exp_f32_e32 v101, v85
	v_add_f32_e32 v72, v113, v112
	v_exp_f32_e32 v117, v65
	v_add_f32_e32 v3, v94, v3
	v_exp_f32_e32 v102, v86
	v_add_f32_e32 v72, v114, v72
	v_exp_f32_e32 v118, v66
	v_add_f32_e32 v3, v95, v3
	v_exp_f32_e32 v103, v87
	v_add_f32_e32 v72, v115, v72
	v_exp_f32_e32 v119, v67
	v_add_f32_e32 v3, v100, v3
	v_exp_f32_e32 v104, v76
	v_add_f32_e32 v64, v116, v72
	v_exp_f32_e32 v120, v60
	v_add_f32_e32 v3, v101, v3
	v_exp_f32_e32 v105, v77
	v_add_f32_e32 v64, v117, v64
	v_exp_f32_e32 v121, v61
	v_add_f32_e32 v3, v102, v3
	v_exp_f32_e32 v106, v78
	v_add_f32_e32 v64, v118, v64
	v_exp_f32_e32 v122, v62
	v_add_f32_e32 v3, v103, v3
	v_exp_f32_e32 v107, v79
	v_add_f32_e32 v64, v119, v64
	v_exp_f32_e32 v123, v63
	v_add_f32_e32 v3, v104, v3
	v_exp_f32_e32 v108, v88
	v_add_f32_e32 v60, v120, v64
	v_exp_f32_e32 v156, v68
	v_add_f32_e32 v3, v105, v3
	v_exp_f32_e32 v109, v89
	v_add_f32_e32 v60, v121, v60
	v_exp_f32_e32 v157, v69
	v_add_f32_e32 v3, v106, v3
	v_exp_f32_e32 v110, v90
	v_add_f32_e32 v60, v122, v60
	v_exp_f32_e32 v158, v70
	v_add_f32_e32 v3, v107, v3
	v_exp_f32_e32 v111, v91
	v_add_f32_e32 v60, v123, v60
	v_exp_f32_e32 v159, v71
	v_add_f32_e32 v3, v108, v3
	v_add_f32_e32 v60, v156, v60
	v_add_f32_e32 v3, v109, v3
	v_add_f32_e32 v60, v157, v60
	v_add_f32_e32 v3, v110, v3
	v_add_f32_e32 v60, v158, v60
	v_add_f32_e32 v3, v111, v3
	v_add_f32_e32 v202, v159, v60
	v_add_f32_e32 v3, v191, v3
	v_mov_b32_e32 v201, v2
	v_mov_b32_e32 v200, v190
	v_mov_b32_e32 v192, v189
.LBB0_1183:
	v_add3_u32 v248, s17, v167, v184
	ds_read_b64_tr_b16 v[76:77], v248 offset:18432
	ds_read_b64_tr_b16 v[78:79], v248 offset:20736
	ds_read_b64_tr_b16 v[80:81], v248 offset:18464
	ds_read_b64_tr_b16 v[82:83], v248 offset:20768
	ds_read_b64_tr_b16 v[84:85], v248 offset:18496
	ds_read_b64_tr_b16 v[86:87], v248 offset:20800
	ds_read_b64_tr_b16 v[88:89], v248 offset:18528
	ds_read_b64_tr_b16 v[90:91], v248 offset:20832
	ds_read_b64_tr_b16 v[194:195], v248 offset:23040
	ds_read_b64_tr_b16 v[196:197], v248 offset:25344
	ds_read_b64_tr_b16 v[206:207], v248 offset:23072
	ds_read_b64_tr_b16 v[208:209], v248 offset:25376
	ds_read_b64_tr_b16 v[210:211], v248 offset:23104
	ds_read_b64_tr_b16 v[212:213], v248 offset:25408
	ds_read_b64_tr_b16 v[230:231], v248 offset:23136
	ds_read_b64_tr_b16 v[232:233], v248 offset:25440
	v_cvt_pk_bf16_f32 v60, v92, v93
	v_cvt_pk_bf16_f32 v61, v94, v95
	v_cvt_pk_bf16_f32 v62, v100, v101
	v_cvt_pk_bf16_f32 v63, v102, v103
	v_cvt_pk_bf16_f32 v64, v112, v113
	v_cvt_pk_bf16_f32 v65, v114, v115
	v_cvt_pk_bf16_f32 v66, v116, v117
	v_cvt_pk_bf16_f32 v67, v118, v119
	v_cvt_pk_bf16_f32 v68, v104, v105
	v_cvt_pk_bf16_f32 v69, v106, v107
	v_cvt_pk_bf16_f32 v70, v108, v109
	v_cvt_pk_bf16_f32 v71, v110, v111
	v_cvt_pk_bf16_f32 v72, v120, v121
	v_cvt_pk_bf16_f32 v73, v122, v123
	v_cvt_pk_bf16_f32 v74, v156, v157
	v_cvt_pk_bf16_f32 v75, v158, v159
	s_cmp_gt_i32 s16, -1
	s_cselect_b64 s[0:1], -1, 0
	s_add_i32 s2, s15, 1
	s_cmp_lg_u32 s15, 2
	s_cselect_b32 s15, s2, 0
	s_and_b64 vcc, exec, s[0:1]
	v_add_f32_e32 v2, v201, v202
	s_waitcnt lgkmcnt(0)
	v_mfma_f32_16x16x32_bf16 v[36:39], v[76:79], v[60:63], v[36:39]
	v_mfma_f32_16x16x32_bf16 v[20:23], v[76:79], v[64:67], v[20:23]
	v_mfma_f32_16x16x32_bf16 v[48:51], v[80:83], v[60:63], v[48:51]
	v_mfma_f32_16x16x32_bf16 v[24:27], v[80:83], v[64:67], v[24:27]
	v_mfma_f32_16x16x32_bf16 v[52:55], v[84:87], v[60:63], v[52:55]
	v_mfma_f32_16x16x32_bf16 v[28:31], v[84:87], v[64:67], v[28:31]
	v_mfma_f32_16x16x32_bf16 v[56:59], v[88:91], v[60:63], v[56:59]
	v_mfma_f32_16x16x32_bf16 v[32:35], v[88:91], v[64:67], v[32:35]
	v_mfma_f32_16x16x32_bf16 v[36:39], v[194:197], v[68:71], v[36:39]
	v_mfma_f32_16x16x32_bf16 v[20:23], v[194:197], v[72:75], v[20:23]
	v_mfma_f32_16x16x32_bf16 v[48:51], v[206:209], v[68:71], v[48:51]
	v_mfma_f32_16x16x32_bf16 v[24:27], v[206:209], v[72:75], v[24:27]
	v_mfma_f32_16x16x32_bf16 v[52:55], v[210:213], v[68:71], v[52:55]
	v_mfma_f32_16x16x32_bf16 v[28:31], v[210:213], v[72:75], v[28:31]
	v_mfma_f32_16x16x32_bf16 v[56:59], v[230:233], v[68:71], v[56:59]
	v_mfma_f32_16x16x32_bf16 v[32:35], v[230:233], v[72:75], v[32:35]
	s_nop 1
	v_cndmask_b32_e64 v60, 0, 1, s[0:1]
	v_xor_b32_e32 v187, v187, v60
	s_cbranch_vccz .LBB0_1000
	v_mov_b32_e32 v189, v192
	v_mov_b32_e32 v190, v200
	v_mov_b32_e32 v191, v3
	s_mov_b32 s2, s16
	s_mov_b64 s[0:1], s[10:11]
	s_branch .LBB0_1164
